# static s_setprio 1 for waves 4-7 (map 1) across the attention far/near loops, reset to 0 at the tail
# baseline (speedup 1.0000x reference)
; template <bool NEAR>
; DI void attn_qk(f32x16& s0, f32x16& s1, ldsp_t kb, const int* kro, const bf16x8* qf, int dtile, const float* tb2, int hi, int qg, int r32) {
;     bf16x8 a[8];
; #pragma unroll
;     for (int ks = 0; ks < 4; ++ks) { a[2 * ks] = *(const __attribute__((address_space(3))) bf16x8*)(kb + kro[ks]); a[2 * ks + 1] = *(const __attribute__((address_space(3))) bf16x8*)(kb + kro[ks] + 8192); }
;     if (!NEAR) {
;         const float c0 = tb2[0];
; #pragma unroll
;         for (int k = 0; k < 16; ++k) { s0[k] = c0; s1[k] = c0; }
;     } else {
;         const int base = dtile * 64 + 8 * hi - (qg & 1) * 32 - r32 + 128;
; #pragma unroll
; DI void attn_mfma_phase(PP P, int l, unsigned char* lds, int G, int cid) {
;     ...
;         const int w = u & 255, i = u >> 8, bh = (w & 7) * 4 + (w >> 6), r = (w >> 3) & 7, b = bh >> 3, h = bh & 7;
;         const int j = (i >> 1) * 16 + ((i & 1) ? 15 - r : r);
;         const int mychunk = 2 * j + (qg >> 1), qpos = j * 128 + qg * 32 + r32;
;         float mb = 0.f;
;         for (int k = 0; k < 32; ++k) mb = fmaxf(mb, fabsf(P->in[23][k * 8 + h]));
;         const float smax2 = (8.f * mq * mk + mb) * LOG2E;
;         __syncthreads();
;         if (tid < 192) tb2[tid] = P->in[23][t5_bucket(tid - 128) * 8 + h] * LOG2E - smax2;
;         bf16x8 qf[4];
;         { const bf16_t* qp = Zq + ((size_t)b * SEQ + qpos) * 1024 + h * 128 + map * 64 + 8 * hi;
; #pragma unroll
;           for (int ks = 0; ks < 4; ++ks) qf[ks] = *(const bf16x8*)(qp + ks * 16); }
;         f32x16 o[4];
; #pragma unroll
;         for (int et = 0; et < 4; ++et)
; #pragma unroll
;             for (int k = 0; k < 16; ++k) o[et][k] = 0.f;
;         float lsum = 0.f;
;         const bf16_t* kg[2]; const bf16_t* vg[2];
; #pragma unroll
;         for (int i2 = 0; i2 < 2; ++i2) { const int blk = wave * 2 + i2;
;             { const int row = blk * 4 + (lane >> 4), c = (lane & 15) ^ (row & 15); kg[i2] = Zk + ((size_t)b * SEQ + row) * 1024 + h * 128 + c * 8; }
;             { const int row = blk * 8 + (lane >> 3), c = (lane & 7) ^ ((row >> 1) & 7); vg[i2] = VT + ((size_t)bh * 128 + row) * SEQ + c * 8; } }
;         const int dw = wave * 2048;
;     ...
;         AT_LOADK(0); AT_LOADV(0); AT_LOADK(1);
;         __syncthreads();
;         f32x16 sc0, sc1, sn0, sn1;
;         attn_qk<true>(sc0, sc1, ldsl, kro, qf, 0 - mychunk, tb2, hi, qg, r32);
.LBB0_211:
	s_or_b64 exec, exec, s[12:13]
	s_lshr_b32 s5, s82, 6
	s_and_b32 s6, s67, -4
	s_and_b32 s5, s5, 3
	s_or_b32 s5, s6, s5
	s_lshl_b32 s4, s67, 20
	s_and_b32 s5, s5, 7
	s_bfe_u32 s6, s82, 0x30003
	s_ashr_i32 s42, s82, 5
	s_and_b32 s4, s4, 0x1800000
	s_lshl_b32 s5, s5, 8
	s_and_b32 s9, s42, -16
	s_and_b32 s10, s82, 0x100
	s_xor_b32 s11, s6, 15
	s_cmp_eq_u32 s10, 0
	s_cselect_b32 s43, s6, s11
	s_or_b32 s6, s43, s9
	s_lshl_b32 s12, s6, 7
	s_waitcnt vmcnt(30)
	v_or_b32_e32 v2, s12, v203
	s_lshl_b32 s8, s8, 9
	s_and_b32 s20, s8, 0x3000
	s_waitcnt vmcnt(29)
	v_ashrrev_i32_e32 v3, 31, v2
	v_lshl_add_u64 v[192:193], v[2:3], 0, s[20:21]
	v_lshlrev_b64 v[2:3], 11, v[192:193]
	v_lshl_add_u64 v[2:3], s[46:47], 0, v[2:3]
	s_lshl_b32 s8, s39, 8
	s_mov_b32 s9, s21
	v_lshl_add_u64 v[2:3], v[2:3], 0, s[8:9]
	v_lshl_add_u64 v[2:3], s[16:17], 1, v[2:3]
	v_lshlrev_b32_e32 v0, 1, v162
	v_lshl_add_u64 v[2:3], v[2:3], 0, v[0:1]
	global_load_dwordx4 v[156:159], v[2:3], off
	global_load_dwordx4 v[152:155], v[2:3], off offset:32
	global_load_dwordx4 v[148:151], v[2:3], off offset:64
	global_load_dwordx4 v[144:147], v[2:3], off offset:96
	s_lshl_b32 s13, s6, 1
	s_or_b32 s10, s13, s60
	s_add_u32 s8, s28, s8
	s_addc_u32 s9, s29, 0
	s_lshl_b32 s84, s7, 7
	s_mov_b32 s85, s21
	s_waitcnt vmcnt(31)
	v_lshl_add_u64 v[4:5], s[84:85], 0, v[174:175]
	v_lshl_add_u64 v[2:3], s[20:21], 0, v[172:173]
	v_lshlrev_b64 v[4:5], 13, v[4:5]
	v_lshlrev_b64 v[2:3], 11, v[2:3]
	v_lshl_add_u64 v[194:195], v[180:181], 0, v[4:5]
	v_lshl_add_u64 v[4:5], s[20:21], 0, v[176:177]
	v_lshl_add_u64 v[2:3], s[8:9], 0, v[2:3]
	v_mov_b32_e32 v189, v1
	v_lshlrev_b64 v[4:5], 11, v[4:5]
	s_mov_b32 m0, s65
	v_lshl_add_u64 v[2:3], v[2:3], 0, v[188:189]
	v_lshl_add_u64 v[4:5], s[8:9], 0, v[4:5]
	v_mov_b32_e32 v191, v1
	v_lshl_add_u64 v[4:5], v[4:5], 0, v[190:191]
	s_waitcnt vmcnt(29)
	v_lshl_add_u64 v[6:7], s[84:85], 0, v[178:179]
	global_load_lds_dwordx4 v[2:3], off
	s_add_i32 m0, s65, 0x400
	v_lshlrev_b64 v[6:7], 13, v[6:7]
	global_load_lds_dwordx4 v[4:5], off
	s_add_i32 m0, s65, 0x10000
	v_lshl_add_u64 v[196:197], v[182:183], 0, v[6:7]
	global_load_lds_dwordx4 v[194:195], off
	s_mov_b32 m0, s73
	v_lshl_add_u64 v[2:3], v[2:3], 0, s[34:35]
	global_load_lds_dwordx4 v[196:197], off
	s_add_i32 m0, s65, 0x4000
	v_lshl_or_b32 v0, s10, 6, v216
	global_load_lds_dwordx4 v[2:3], off
	v_lshl_add_u64 v[4:5], v[4:5], 0, s[34:35]
	s_mov_b32 m0, s80
	v_sub_u32_e32 v0, v162, v0
	global_load_lds_dwordx4 v[4:5], off
	s_waitcnt vmcnt(0)
	s_add_i32 m0, s65, 0x14000
	v_lshl_add_u64 v[6:7], v[194:195], 0, s[22:23]
	global_load_lds_dwordx4 v[6:7], off
	s_add_i32 m0, s65, 0x14400
	v_lshl_add_u64 v[8:9], v[196:197], 0, s[22:23]
	global_load_lds_dwordx4 v[8:9], off
	s_add_i32 m0, s65, 0x8000
	v_lshl_add_u64 v[2:3], v[2:3], 0, s[34:35]
	global_load_lds_dwordx4 v[2:3], off
	s_add_i32 m0, s65, 0x8400
	v_lshl_add_u64 v[4:5], v[4:5], 0, s[34:35]
	global_load_lds_dwordx4 v[4:5], off
	s_add_i32 m0, s65, 0x18000
	v_lshl_add_u64 v[6:7], v[6:7], 0, s[22:23]
	global_load_lds_dwordx4 v[6:7], off
	s_add_i32 m0, s65, 0x18400
	v_lshl_add_u64 v[8:9], v[8:9], 0, s[22:23]
	global_load_lds_dwordx4 v[8:9], off
	s_add_i32 m0, s65, 0xc000
	v_lshl_add_u64 v[2:3], v[2:3], 0, s[34:35]
	global_load_lds_dwordx4 v[2:3], off
	s_add_i32 m0, s65, 0xc400
	v_lshl_add_u64 v[4:5], v[4:5], 0, s[34:35]
	global_load_lds_dwordx4 v[4:5], off
	v_add_u32_e32 v10, 0x80, v0
	v_max_i32_e32 v11, 0, v10
	v_max_i32_e32 v10, 0xffffffe0, v10
	v_add_u32_e32 v12, 0x81, v0
	v_add_u32_e32 v14, 0x82, v0
	v_add_u32_e32 v16, 0x83, v0
	v_add_u32_e32 v191, 0, v171
	v_lshl_add_u32 v11, v11, 2, s61
	v_lshl_add_u32 v10, v10, 2, s61
	v_max_i32_e32 v13, 0, v12
	v_max_i32_e32 v12, 0xffffffe0, v12
	v_max_i32_e32 v15, 0, v14
	v_max_i32_e32 v14, 0xffffffe0, v14
	v_max_i32_e32 v17, 0, v16
	v_max_i32_e32 v16, 0xffffffe0, v16
	s_waitcnt lgkmcnt(0)
	s_barrier
	ds_read_b128 v[2:5], v191
	ds_read_b128 v[6:9], v191 offset:8192
	v_lshl_add_u32 v13, v13, 2, s61
	v_lshl_add_u32 v12, v12, 2, s61
	v_lshl_add_u32 v15, v15, 2, s61
	v_lshl_add_u32 v14, v14, 2, s61
	v_lshl_add_u32 v17, v17, 2, s61
	v_lshl_add_u32 v16, v16, 2, s61
	ds_read_b32 v96, v11
	ds_read_b32 v80, v10 offset:128
	ds_read_b32 v97, v13
	ds_read_b32 v81, v12 offset:128
	ds_read_b32 v98, v15
	ds_read_b32 v82, v14 offset:128
	ds_read_b32 v99, v17
	ds_read_b32 v83, v16 offset:128
	v_add_u32_e32 v10, 0x84, v0
	v_max_i32_e32 v11, 0, v10
	v_max_i32_e32 v10, 0xffffffe0, v10
	v_add_u32_e32 v12, 0x85, v0
	v_add_u32_e32 v14, 0x86, v0
	v_add_u32_e32 v16, 0x87, v0
	v_lshl_add_u32 v11, v11, 2, s61
	v_lshl_add_u32 v10, v10, 2, s61
	v_max_i32_e32 v13, 0, v12
	v_max_i32_e32 v12, 0xffffffe0, v12
	v_max_i32_e32 v15, 0, v14
	v_max_i32_e32 v14, 0xffffffe0, v14
	v_max_i32_e32 v17, 0, v16
	v_max_i32_e32 v16, 0xffffffe0, v16
	v_lshl_add_u32 v13, v13, 2, s61
	v_lshl_add_u32 v12, v12, 2, s61
	v_lshl_add_u32 v15, v15, 2, s61
	v_lshl_add_u32 v14, v14, 2, s61
	v_lshl_add_u32 v17, v17, 2, s61
	v_lshl_add_u32 v16, v16, 2, s61
	ds_read_b32 v100, v11
	ds_read_b32 v84, v10 offset:128
	ds_read_b32 v101, v13
	ds_read_b32 v85, v12 offset:128
	ds_read_b32 v102, v15
	ds_read_b32 v86, v14 offset:128
	ds_read_b32 v103, v17
	ds_read_b32 v87, v16 offset:128
	v_add_u32_e32 v10, 0x90, v0
	v_max_i32_e32 v11, 0, v10
	v_max_i32_e32 v10, 0xffffffe0, v10
	v_add_u32_e32 v12, 0x91, v0
	v_add_u32_e32 v14, 0x92, v0
	v_add_u32_e32 v16, 0x93, v0
	v_lshl_add_u32 v11, v11, 2, s61
	v_lshl_add_u32 v10, v10, 2, s61
	v_max_i32_e32 v13, 0, v12
	v_max_i32_e32 v12, 0xffffffe0, v12
	v_max_i32_e32 v15, 0, v14
	v_max_i32_e32 v14, 0xffffffe0, v14
	v_max_i32_e32 v17, 0, v16
	v_max_i32_e32 v16, 0xffffffe0, v16
	v_lshl_add_u32 v13, v13, 2, s61
	v_lshl_add_u32 v12, v12, 2, s61
	v_lshl_add_u32 v15, v15, 2, s61
	v_lshl_add_u32 v14, v14, 2, s61
	v_lshl_add_u32 v17, v17, 2, s61
	v_lshl_add_u32 v16, v16, 2, s61
	ds_read_b32 v104, v11
	ds_read_b32 v88, v10 offset:128
	ds_read_b32 v105, v13
	ds_read_b32 v89, v12 offset:128
	ds_read_b32 v106, v15
	ds_read_b32 v90, v14 offset:128
	ds_read_b32 v107, v17
	ds_read_b32 v91, v16 offset:128
	v_add_u32_e32 v10, 0x94, v0
	v_max_i32_e32 v11, 0, v10
	v_add_u32_e32 v12, 0x95, v0
	v_add_u32_e32 v14, 0x96, v0
	v_add_u32_e32 v0, 0x97, v0
	v_lshl_add_u32 v11, v11, 2, s61
	v_max_i32_e32 v13, 0, v12
	v_max_i32_e32 v15, 0, v14
	v_max_i32_e32 v16, 0, v0
	v_lshl_add_u32 v13, v13, 2, s61
	v_lshl_add_u32 v15, v15, 2, s61
	v_lshl_add_u32 v16, v16, 2, s61
	ds_read_b32 v108, v11
	ds_read_b32 v109, v13
	ds_read_b32 v110, v15
	ds_read_b32 v111, v16
	v_max_i32_e32 v10, 0xffffffe0, v10
	v_max_i32_e32 v12, 0xffffffe0, v12
	v_lshl_add_u32 v10, v10, 2, s61
	v_lshl_add_u32 v12, v12, 2, s61
	v_max_i32_e32 v14, 0xffffffe0, v14
	v_max_i32_e32 v0, 0xffffffe0, v0
	v_add_u32_e32 v229, 0, v200
	v_lshl_add_u32 v11, v14, 2, s61
	v_lshl_add_u32 v0, v0, 2, s61
	ds_read_b32 v92, v10 offset:128
	s_waitcnt lgkmcnt(1)
; #define AT_LOADK(t) do { AT_DMA(kg[0] + (size_t)(t) * 65536, ldsl + ((t) & 1) * AT_KS + dw); AT_DMA(kg[1] + (size_t)(t) * 65536, ldsl + ((t) & 1) * AT_KS + dw + 1024); } while (0)
; #define AT_LOADV(t) do { AT_DMA(vg[0] + (t) * 64, ldsl + AT_V0 + ((t) & 1) * AT_KS + dw); AT_DMA(vg[1] + (t) * 64, ldsl + AT_V0 + ((t) & 1) * AT_KS + dw + 1024); } while (0)
; DI void attn_pv(f32x16& s0, f32x16& s1, ldsp_t vb, const int* vro, f32x16* o, float& lsum) {
; #pragma unroll
;     for (int k = 0; k < 16; ++k) { s0[k] = __builtin_amdgcn_exp2f(s0[k]); s1[k] = __builtin_amdgcn_exp2f(s1[k]); }
;     float ps = 0.f;
; #pragma unroll
;     for (int k = 0; k < 16; ++k) ps += s0[k] + s1[k];
;     lsum += ps;
;     bf16x8 pk[4]; pk[0] = pack8(s0, 0); pk[1] = pack8(s0, 1); pk[2] = pack8(s1, 0); pk[3] = pack8(s1, 1);
; #pragma unroll
;     for (int kk = 0; kk < 4; ++kk)
; #pragma unroll
;         for (int et = 0; et < 4; ++et) {
;             const bf16x8 a = *(const __attribute__((address_space(3))) bf16x8*)(vb + vro[kk] + et * 4096);
; DI void attn_mfma_phase(PP P, int l, unsigned char* lds, int G, int cid) {
;     ...
;         f32x16 o[4];
; #pragma unroll
;         for (int et = 0; et < 4; ++et)
; #pragma unroll
;             for (int k = 0; k < 16; ++k) o[et][k] = 0.f;
;         float lsum = 0.f;
;     ...
;         const int nfar = 2 * j - 3;
;         int kt = 0;
;         for (; kt < nfar; ++kt) {
;             AT_LOADK(kt + 2); AT_LOADV(kt + 1);
;             attn_qk<false>(sn0, sn1, ldsl + ((kt + 1) & 1) * AT_KS, kro, qf, 0, tb2, hi, qg, r32);
;             attn_pv(sc0, sc1, ldsl + (kt & 1) * AT_KS, vro, o, lsum);
;             sc0 = sn0; sc1 = sn1;
	v_mfma_f32_32x32x16_bf16 v[96:111], v[2:5], v[156:159], v[96:111]
	ds_read_b32 v93, v12 offset:128
	ds_read_b32 v94, v11 offset:128
	ds_read_b32 v95, v0 offset:128
	ds_read_b128 v[2:5], v229
	v_add_u32_e32 v230, 0, v201
	v_add_u32_e32 v231, 0, v202
	s_mov_b32 s38, 0
	s_cmp_lt_i32 s6, 2
	s_waitcnt lgkmcnt(0)
	v_mfma_f32_32x32x16_bf16 v[96:111], v[2:5], v[152:155], v[96:111]
	ds_read_b128 v[2:5], v229 offset:8192
	v_mfma_f32_32x32x16_bf16 v[80:95], v[6:9], v[156:159], v[80:95]
	s_waitcnt lgkmcnt(0)
	v_mfma_f32_32x32x16_bf16 v[80:95], v[2:5], v[152:155], v[80:95]
	ds_read_b128 v[2:5], v230
	s_waitcnt lgkmcnt(0)
	v_mfma_f32_32x32x16_bf16 v[96:111], v[2:5], v[148:151], v[96:111]
	ds_read_b128 v[2:5], v230 offset:8192
	s_waitcnt lgkmcnt(0)
	v_mfma_f32_32x32x16_bf16 v[80:95], v[2:5], v[148:151], v[80:95]
	ds_read_b128 v[2:5], v231
	s_waitcnt lgkmcnt(0)
	v_mfma_f32_32x32x16_bf16 v[96:111], v[2:5], v[144:147], v[96:111]
	ds_read_b128 v[2:5], v231 offset:8192
	s_waitcnt lgkmcnt(0)
	v_mfma_f32_32x32x16_bf16 v[80:95], v[2:5], v[144:147], v[80:95]
	s_cbranch_scc1 .LBB0_215
	s_add_u32 s6, s4, s5
	s_addc_u32 s7, 0, 0
	v_lshl_add_u64 v[10:11], v[184:185], 0, s[6:7]
	v_lshl_add_u64 v[12:13], v[186:187], 0, s[6:7]
	s_lshl_b32 s6, s42, 1
	s_andn2_b32 s6, s6, 31
	s_lshl_b32 s7, s43, 1
	s_or_b32 s6, s6, s7
	s_add_i32 s6, s6, -3
	s_max_i32 s38, s6, 1
	s_sub_i32 s7, 0, s38
	v_mov_b32_e32 v189, 0
	s_movk_i32 s6, 0x4000
	s_mov_b32 s20, 0xc0
	v_mov_b32_e32 v232, s7
	v_mov_b32_e32 v64, 0
	v_mov_b32_e32 v65, v189
	v_mov_b32_e32 v66, v189
	v_mov_b32_e32 v67, v189
	v_mov_b32_e32 v68, v189
	v_mov_b32_e32 v69, v189
	v_mov_b32_e32 v70, v189
	v_mov_b32_e32 v71, v189
	v_mov_b32_e32 v72, v189
	v_mov_b32_e32 v73, v189
	v_mov_b32_e32 v74, v189
	v_mov_b32_e32 v75, v189
	v_mov_b32_e32 v76, v189
	v_mov_b32_e32 v77, v189
	v_mov_b32_e32 v78, v189
	v_mov_b32_e32 v79, v189
	v_mov_b32_e32 v48, 0
	v_mov_b32_e32 v49, v189
	v_mov_b32_e32 v50, v189
	v_mov_b32_e32 v51, v189
	v_mov_b32_e32 v52, v189
	v_mov_b32_e32 v53, v189
	v_mov_b32_e32 v54, v189
	v_mov_b32_e32 v55, v189
	v_mov_b32_e32 v56, v189
	v_mov_b32_e32 v57, v189
	v_mov_b32_e32 v58, v189
	v_mov_b32_e32 v59, v189
	v_mov_b32_e32 v60, v189
	v_mov_b32_e32 v61, v189
	v_mov_b32_e32 v62, v189
	v_mov_b32_e32 v63, v189
	v_mov_b32_e32 v32, 0
	v_mov_b32_e32 v33, v189
	v_mov_b32_e32 v34, v189
	v_mov_b32_e32 v35, v189
	v_mov_b32_e32 v36, v189
	v_mov_b32_e32 v37, v189
	v_mov_b32_e32 v38, v189
	v_mov_b32_e32 v39, v189
	v_mov_b32_e32 v40, v189
	v_mov_b32_e32 v41, v189
	v_mov_b32_e32 v42, v189
	v_mov_b32_e32 v43, v189
	v_mov_b32_e32 v44, v189
	v_mov_b32_e32 v45, v189
	v_mov_b32_e32 v46, v189
	v_mov_b32_e32 v47, v189
	v_mov_b32_e32 v16, 0
	v_mov_b32_e32 v17, v189
	v_mov_b32_e32 v18, v189
	v_mov_b32_e32 v19, v189
	v_mov_b32_e32 v20, v189
	v_mov_b32_e32 v21, v189
	v_mov_b32_e32 v22, v189
	v_mov_b32_e32 v23, v189
	v_mov_b32_e32 v24, v189
	v_mov_b32_e32 v25, v189
	v_mov_b32_e32 v26, v189
	v_mov_b32_e32 v27, v189
	v_mov_b32_e32 v28, v189
	v_mov_b32_e32 v29, v189
	v_mov_b32_e32 v30, v189
	v_mov_b32_e32 v31, v189
	v_mov_b32_e32 v0, s61
	ds_read_b32 v112, v0
	v_exp_f32_e32 v14, v96
	v_exp_f32_e32 v15, v97
	v_exp_f32_e32 v168, v98
	v_exp_f32_e32 v169, v99
	v_exp_f32_e32 v198, v100
	v_exp_f32_e32 v199, v101
	v_exp_f32_e32 v238, v102
	v_exp_f32_e32 v239, v103
	v_cvt_pk_bf16_f32 v128, v14, v15
	v_cvt_pk_bf16_f32 v129, v168, v169
	v_add_f32_e32 v14, v14, v15
	v_add_f32_e32 v168, v168, v169
	v_cvt_pk_bf16_f32 v130, v198, v199
	v_cvt_pk_bf16_f32 v131, v238, v239
	v_add_f32_e32 v198, v198, v199
	v_add_f32_e32 v238, v238, v239
	v_add_f32_e32 v14, v14, v168
	v_add_f32_e32 v198, v198, v238
	v_add_f32_e32 v235, v14, v198
	s_waitcnt lgkmcnt(0)
	v_mov_b32_e32 v113, v112
	v_mov_b32_e32 v114, v112
	v_mov_b32_e32 v115, v112
	v_mov_b32_e32 v116, v112
	v_mov_b32_e32 v117, v112
	v_mov_b32_e32 v118, v112
	v_mov_b32_e32 v119, v112
	v_mov_b32_e32 v120, v112
	v_mov_b32_e32 v121, v112
	v_mov_b32_e32 v122, v112
	v_mov_b32_e32 v123, v112
	v_mov_b32_e32 v124, v112
	v_mov_b32_e32 v125, v112
	v_mov_b32_e32 v126, v112
	v_mov_b32_e32 v127, v112
	s_cmp_lg_u64 s[48:49], 0
	s_cbranch_scc0 .Lattn_noprio_far
	s_setprio 1
.Lattn_noprio_far:
.LBB0_213:
	s_add_i32 s7, s6, 0xffffc000
	s_and_b32 s7, s7, 0xc000
	s_and_b32 s10, s6, 0xc000
	v_add_u32_e32 v248, s7, v222
	v_add_u32_e32 v249, s7, v223
	s_add_i32 s11, s6, 0x8000
	s_and_b32 s11, s11, 0xc000
	s_add_i32 s11, s11, s65
	ds_read_b128 v[2:5], v248 offset:32768
	ds_read_b128 v[6:9], v248 offset:36864
	ds_read_b128 v[136:139], v248 offset:40960
	ds_read_b128 v[140:143], v248 offset:45056
	ds_read_b128 v[240:243], v249 offset:32768
	s_lshl_b64 s[8:9], s[20:21], 1
	s_add_i32 m0, s7, s64
	v_lshl_add_u64 v[236:237], v[194:195], 0, s[8:9]
	global_load_lds_dwordx4 v[12:13], off
	s_add_i32 m0, m0, 0x400
	v_add_u32_e32 v252, s10, v171
	global_load_lds_dwordx4 v[10:11], off
	s_add_i32 m0, s11, 0x10000
	v_add_u32_e32 v253, s10, v200
	global_load_lds_dwordx4 v[236:237], off
	v_lshl_add_u64 v[236:237], v[196:197], 0, s[8:9]
	s_add_i32 m0, s11, 0x10400
	v_add_u32_e32 v233, s10, v201
	global_load_lds_dwordx4 v[236:237], off
	v_add_u32_e32 v234, s10, v202
	v_add_u32_e32 v250, s7, v224
	v_add_u32_e32 v251, s7, v225
	v_add_f32_e32 v189, v189, v235
	s_addk_i32 s6, 0x4000
	s_add_i32 s20, s20, 64
	v_exp_f32_e32 v14, v104
	v_exp_f32_e32 v15, v105
	v_exp_f32_e32 v168, v106
	v_exp_f32_e32 v169, v107
	v_exp_f32_e32 v198, v108
	v_exp_f32_e32 v199, v109
	v_exp_f32_e32 v238, v110
	v_exp_f32_e32 v239, v111
	s_waitcnt lgkmcnt(4)
	v_mfma_f32_32x32x16_bf16 v[64:79], v[2:5], v[128:131], v[64:79]
	ds_read_b128 v[244:247], v249 offset:36864
	v_cvt_pk_bf16_f32 v132, v14, v15
	v_cvt_pk_bf16_f32 v133, v168, v169
	v_add_f32_e32 v14, v14, v15
	v_add_f32_e32 v168, v168, v169
	s_waitcnt lgkmcnt(4)
; #define MFMA32(a, b, c) __builtin_amdgcn_mfma_f32_32x32x16_bf16((a), (b), (c), 0, 0, 0)
; #define AT_LOADK(t) do { AT_DMA(kg[0] + (size_t)(t) * 65536, ldsl + ((t) & 1) * AT_KS + dw); AT_DMA(kg[1] + (size_t)(t) * 65536, ldsl + ((t) & 1) * AT_KS + dw + 1024); } while (0)
; #define AT_LOADV(t) do { AT_DMA(vg[0] + (t) * 64, ldsl + AT_V0 + ((t) & 1) * AT_KS + dw); AT_DMA(vg[1] + (t) * 64, ldsl + AT_V0 + ((t) & 1) * AT_KS + dw + 1024); } while (0)
; template <bool NEAR>
; DI void attn_qk(f32x16& s0, f32x16& s1, ldsp_t kb, const int* kro, const bf16x8* qf, int dtile, const float* tb2, int hi, int qg, int r32) {
;     ...
;     for (int ks = 0; ks < 4; ++ks) { s0 = MFMA32(a[2 * ks], qf[ks], s0); s1 = MFMA32(a[2 * ks + 1], qf[ks], s1); }
; }
; DI void attn_pv(f32x16& s0, f32x16& s1, ldsp_t vb, const int* vro, f32x16* o, float& lsum) {
; #pragma unroll
;     for (int k = 0; k < 16; ++k) { s0[k] = __builtin_amdgcn_exp2f(s0[k]); s1[k] = __builtin_amdgcn_exp2f(s1[k]); }
;     float ps = 0.f;
; #pragma unroll
;     for (int k = 0; k < 16; ++k) ps += s0[k] + s1[k];
;     lsum += ps;
;     bf16x8 pk[4]; pk[0] = pack8(s0, 0); pk[1] = pack8(s0, 1); pk[2] = pack8(s1, 0); pk[3] = pack8(s1, 1);
; #pragma unroll
;     for (int kk = 0; kk < 4; ++kk)
; #pragma unroll
;         for (int et = 0; et < 4; ++et) {
;             const bf16x8 a = *(const __attribute__((address_space(3))) bf16x8*)(vb + vro[kk] + et * 4096);
;             o[et] = MFMA32(a, pk[kk], o[et]);
;         }
; DI void attn_mfma_phase(PP P, int l, unsigned char* lds, int G, int cid) {
;     ...
;         for (; kt < nfar; ++kt) {
;             AT_LOADK(kt + 2); AT_LOADV(kt + 1);
;             attn_qk<false>(sn0, sn1, ldsl + ((kt + 1) & 1) * AT_KS, kro, qf, 0, tb2, hi, qg, r32);
;             attn_pv(sc0, sc1, ldsl + (kt & 1) * AT_KS, vro, o, lsum);
;             sc0 = sn0; sc1 = sn1;
;             __syncthreads();
;         }
	v_mfma_f32_32x32x16_bf16 v[48:63], v[6:9], v[128:131], v[48:63]
	ds_read_b128 v[2:5], v249 offset:40960
	v_cvt_pk_bf16_f32 v134, v198, v199
	v_cvt_pk_bf16_f32 v135, v238, v239
	v_add_f32_e32 v198, v198, v199
	v_add_f32_e32 v238, v238, v239
	s_waitcnt lgkmcnt(4)
	v_mfma_f32_32x32x16_bf16 v[32:47], v[136:139], v[128:131], v[32:47]
	ds_read_b128 v[6:9], v249 offset:45056
	v_add_f32_e32 v14, v14, v168
	v_add_f32_e32 v198, v198, v238
	v_add_f32_e32 v14, v14, v198
	v_add_f32_e32 v189, v189, v14
	s_waitcnt lgkmcnt(4)
	v_mfma_f32_32x32x16_bf16 v[16:31], v[140:143], v[128:131], v[16:31]
	ds_read_b128 v[136:139], v252
	v_exp_f32_e32 v14, v80
	v_exp_f32_e32 v15, v81
	v_exp_f32_e32 v168, v82
	s_waitcnt lgkmcnt(4)
	v_mfma_f32_32x32x16_bf16 v[64:79], v[240:243], v[132:135], v[64:79]
	ds_read_b128 v[140:143], v253
	v_exp_f32_e32 v169, v83
	v_exp_f32_e32 v198, v84
	v_exp_f32_e32 v199, v85
	s_waitcnt lgkmcnt(4)
	v_mfma_f32_32x32x16_bf16 v[48:63], v[244:247], v[132:135], v[48:63]
	ds_read_b128 v[240:243], v233
	v_exp_f32_e32 v238, v86
	v_exp_f32_e32 v239, v87
	v_cvt_pk_bf16_f32 v128, v14, v15
	s_waitcnt lgkmcnt(4)
	v_mfma_f32_32x32x16_bf16 v[32:47], v[2:5], v[132:135], v[32:47]
	ds_read_b128 v[244:247], v234
	v_cvt_pk_bf16_f32 v129, v168, v169
	v_add_f32_e32 v14, v14, v15
	v_add_f32_e32 v168, v168, v169
	s_waitcnt lgkmcnt(4)
	v_mfma_f32_32x32x16_bf16 v[16:31], v[6:9], v[132:135], v[16:31]
	ds_read_b128 v[2:5], v250 offset:32768
	v_cvt_pk_bf16_f32 v130, v198, v199
	v_cvt_pk_bf16_f32 v131, v238, v239
	v_add_f32_e32 v198, v198, v199
	s_waitcnt lgkmcnt(4)
	v_mfma_f32_32x32x16_bf16 v[96:111], v[136:139], v[156:159], v[112:127]
	ds_read_b128 v[6:9], v250 offset:36864
	v_add_f32_e32 v238, v238, v239
	v_add_f32_e32 v14, v14, v168
	v_add_f32_e32 v198, v198, v238
	s_waitcnt lgkmcnt(4)
	v_mfma_f32_32x32x16_bf16 v[96:111], v[140:143], v[152:155], v[96:111]
	ds_read_b128 v[136:139], v250 offset:40960
	v_add_f32_e32 v14, v14, v198
	v_add_f32_e32 v189, v189, v14
	s_waitcnt lgkmcnt(4)
	v_mfma_f32_32x32x16_bf16 v[96:111], v[240:243], v[148:151], v[96:111]
	ds_read_b128 v[140:143], v250 offset:45056
	v_exp_f32_e32 v14, v88
	v_exp_f32_e32 v15, v89
	v_exp_f32_e32 v168, v90
	s_waitcnt lgkmcnt(4)
	v_mfma_f32_32x32x16_bf16 v[96:111], v[244:247], v[144:147], v[96:111]
	ds_read_b128 v[240:243], v251 offset:32768
	v_exp_f32_e32 v169, v91
	v_exp_f32_e32 v198, v92
	v_exp_f32_e32 v199, v93
	s_waitcnt lgkmcnt(4)
	v_mfma_f32_32x32x16_bf16 v[64:79], v[2:5], v[128:131], v[64:79]
	ds_read_b128 v[244:247], v251 offset:36864
	v_exp_f32_e32 v238, v94
	v_exp_f32_e32 v239, v95
	v_cvt_pk_bf16_f32 v132, v14, v15
	v_cvt_pk_bf16_f32 v133, v168, v169
	s_waitcnt lgkmcnt(4)
	v_mfma_f32_32x32x16_bf16 v[48:63], v[6:9], v[128:131], v[48:63]
	ds_read_b128 v[2:5], v251 offset:40960
	v_add_f32_e32 v14, v14, v15
	v_add_f32_e32 v168, v168, v169
	v_cvt_pk_bf16_f32 v134, v198, v199
	v_cvt_pk_bf16_f32 v135, v238, v239
	s_waitcnt lgkmcnt(4)
	v_mfma_f32_32x32x16_bf16 v[32:47], v[136:139], v[128:131], v[32:47]
	ds_read_b128 v[6:9], v251 offset:45056
	v_add_f32_e32 v198, v198, v199
	v_add_f32_e32 v238, v238, v239
	v_add_f32_e32 v14, v14, v168
	s_waitcnt lgkmcnt(4)
	v_mfma_f32_32x32x16_bf16 v[16:31], v[140:143], v[128:131], v[16:31]
	ds_read_b128 v[136:139], v252 offset:8192
	v_add_f32_e32 v198, v198, v238
	v_add_f32_e32 v14, v14, v198
	v_add_f32_e32 v189, v189, v14
	s_waitcnt lgkmcnt(4)
	v_mfma_f32_32x32x16_bf16 v[64:79], v[240:243], v[132:135], v[64:79]
	ds_read_b128 v[140:143], v253 offset:8192
	v_exp_f32_e32 v14, v96
	v_exp_f32_e32 v15, v97
	v_exp_f32_e32 v168, v98
	s_waitcnt lgkmcnt(4)
	v_mfma_f32_32x32x16_bf16 v[48:63], v[244:247], v[132:135], v[48:63]
	ds_read_b128 v[240:243], v233 offset:8192
	v_exp_f32_e32 v169, v99
	v_exp_f32_e32 v198, v100
	v_exp_f32_e32 v199, v101
	s_waitcnt lgkmcnt(4)
	v_mfma_f32_32x32x16_bf16 v[32:47], v[2:5], v[132:135], v[32:47]
	ds_read_b128 v[244:247], v234 offset:8192
	v_exp_f32_e32 v238, v102
	v_exp_f32_e32 v239, v103
	v_cvt_pk_bf16_f32 v128, v14, v15
	s_waitcnt lgkmcnt(4)
	v_mfma_f32_32x32x16_bf16 v[16:31], v[6:9], v[132:135], v[16:31]
	v_cvt_pk_bf16_f32 v129, v168, v169
	v_cvt_pk_bf16_f32 v130, v198, v199
	v_cvt_pk_bf16_f32 v131, v238, v239
	s_waitcnt lgkmcnt(3)
	v_mfma_f32_32x32x16_bf16 v[80:95], v[136:139], v[156:159], v[112:127]
	v_add_f32_e32 v14, v14, v15
	v_add_f32_e32 v168, v168, v169
	v_add_f32_e32 v198, v198, v199
	v_add_f32_e32 v238, v238, v239
	s_waitcnt lgkmcnt(2)
	v_mfma_f32_32x32x16_bf16 v[80:95], v[140:143], v[152:155], v[80:95]
	v_add_f32_e32 v14, v14, v168
	v_add_f32_e32 v198, v198, v238
	v_add_f32_e32 v235, v14, v198
	v_add_co_u32_e32 v232, vcc, 1, v232
	s_waitcnt vmcnt(8) lgkmcnt(0)
	s_barrier
	v_mfma_f32_32x32x16_bf16 v[80:95], v[240:243], v[148:151], v[80:95]
	v_lshl_add_u64 v[12:13], v[12:13], 0, s[34:35]
	v_lshl_add_u64 v[10:11], v[10:11], 0, s[34:35]
	s_and_b64 vcc, exec, vcc
	v_mfma_f32_32x32x16_bf16 v[80:95], v[244:247], v[144:147], v[80:95]
	s_cbranch_vccz .LBB0_213
	s_nop 11
	v_mov_b64_e32 v[142:143], v[94:95]
	v_mov_b64_e32 v[126:127], v[110:111]
	v_mov_b64_e32 v[140:141], v[92:93]
	v_mov_b64_e32 v[138:139], v[90:91]
	v_mov_b64_e32 v[136:137], v[88:89]
	v_mov_b64_e32 v[134:135], v[86:87]
	v_mov_b64_e32 v[132:133], v[84:85]
	v_mov_b64_e32 v[130:131], v[82:83]
	v_mov_b64_e32 v[128:129], v[80:81]
	v_mov_b64_e32 v[124:125], v[108:109]
	v_mov_b64_e32 v[122:123], v[106:107]
	v_mov_b64_e32 v[120:121], v[104:105]
	v_mov_b64_e32 v[118:119], v[102:103]
	v_mov_b64_e32 v[116:117], v[100:101]
	v_mov_b64_e32 v[114:115], v[98:99]
	v_mov_b64_e32 v[112:113], v[96:97]
	s_lshl_b32 s83, s39, 7
	s_cmp_ge_i32 s38, s13
	s_cbranch_scc0 .LBB0_216
	s_branch .LBB0_219

; #define MFMA32(a, b, c) __builtin_amdgcn_mfma_f32_32x32x16_bf16((a), (b), (c), 0, 0, 0)
; #define AT_LOADV(t) do { AT_DMA(vg[0] + (t) * 64, ldsl + AT_V0 + ((t) & 1) * AT_KS + dw); AT_DMA(vg[1] + (t) * 64, ldsl + AT_V0 + ((t) & 1) * AT_KS + dw + 1024); } while (0)
; template <bool NEAR>
; DI void attn_qk(f32x16& s0, f32x16& s1, ldsp_t kb, const int* kro, const bf16x8* qf, int dtile, const float* tb2, int hi, int qg, int r32) {
;     bf16x8 a[8];
; #pragma unroll
;     for (int ks = 0; ks < 4; ++ks) { a[2 * ks] = *(const __attribute__((address_space(3))) bf16x8*)(kb + kro[ks]); a[2 * ks + 1] = *(const __attribute__((address_space(3))) bf16x8*)(kb + kro[ks] + 8192); }
;     if (!NEAR) {
;         const float c0 = tb2[0];
; #pragma unroll
;         for (int k = 0; k < 16; ++k) { s0[k] = c0; s1[k] = c0; }
;     } else {
;         const int base = dtile * 64 + 8 * hi - (qg & 1) * 32 - r32 + 128;
; #pragma unroll
;         for (int k = 0; k < 16; ++k) { const int i0 = base + (k & 7) + 16 * (k >> 3), i1 = i0 + 32; s0[k] = tb2[i0 < 0 ? 0 : i0]; s1[k] = tb2[i1 < 0 ? 0 : i1]; }
;     }
; #pragma unroll
;     for (int ks = 0; ks < 4; ++ks) { s0 = MFMA32(a[2 * ks], qf[ks], s0); s1 = MFMA32(a[2 * ks + 1], qf[ks], s1); }
; }
; DI void attn_pv(f32x16& s0, f32x16& s1, ldsp_t vb, const int* vro, f32x16* o, float& lsum) {
; #pragma unroll
;     for (int k = 0; k < 16; ++k) { s0[k] = __builtin_amdgcn_exp2f(s0[k]); s1[k] = __builtin_amdgcn_exp2f(s1[k]); }
;     float ps = 0.f;
; #pragma unroll
;     for (int k = 0; k < 16; ++k) ps += s0[k] + s1[k];
;     lsum += ps;
;     bf16x8 pk[4]; pk[0] = pack8(s0, 0); pk[1] = pack8(s0, 1); pk[2] = pack8(s1, 0); pk[3] = pack8(s1, 1);
; #pragma unroll
;     for (int kk = 0; kk < 4; ++kk)
; #pragma unroll
;         for (int et = 0; et < 4; ++et) {
;             const bf16x8 a = *(const __attribute__((address_space(3))) bf16x8*)(vb + vro[kk] + et * 4096);
;             o[et] = MFMA32(a, pk[kk], o[et]);
;         }
; }
; DI void attn_mfma_phase(PP P, int l, unsigned char* lds, int G, int cid) {
;     ...
;         for (; kt < 2 * j; ++kt) {
;             AT_LOADK(kt + 2); AT_LOADV(kt + 1);
;             attn_qk<true>(sn0, sn1, ldsl + ((kt + 1) & 1) * AT_KS, kro, qf, kt + 1 - mychunk, tb2, hi, qg, r32);
;             attn_pv(sc0, sc1, ldsl + (kt & 1) * AT_KS, vro, o, lsum);
;             sc0 = sn0; sc1 = sn1;
;             __syncthreads();
;         }
.LBB0_216:
	s_lshl_b32 s6, s43, 7
	v_subrev_u32_e32 v0, s6, v228
	s_lshl_b32 s6, s42, 7
	s_and_b32 s6, s6, 0xfffff800
	s_mov_b32 s39, s21
	s_lshl_b32 s84, s38, 6
	v_subrev_u32_e32 v232, s6, v0
	s_lshl_b32 s42, s38, 14
	s_lshl_b64 s[6:7], s[38:39], 17
	s_add_u32 s4, s4, s6
	s_addc_u32 s6, 0, s7
	s_add_u32 s4, s4, s5
	s_addc_u32 s5, s6, 0
	v_lshl_add_u64 v[10:11], v[184:185], 0, s[4:5]
	v_lshl_add_u64 v[12:13], v[186:187], 0, s[4:5]
	s_mov_b32 s4, 0xc0
	v_exp_f32_e32 v14, v96
	v_exp_f32_e32 v15, v97
	v_exp_f32_e32 v168, v98
	v_exp_f32_e32 v169, v99
	v_exp_f32_e32 v198, v100
	v_exp_f32_e32 v199, v101
	v_exp_f32_e32 v238, v102
	v_exp_f32_e32 v239, v103
	v_cvt_pk_bf16_f32 v128, v14, v15
	v_cvt_pk_bf16_f32 v129, v168, v169
	v_add_f32_e32 v14, v14, v15
	v_add_f32_e32 v168, v168, v169
	v_cvt_pk_bf16_f32 v130, v198, v199
	v_cvt_pk_bf16_f32 v131, v238, v239
	v_add_f32_e32 v198, v198, v199
	v_add_f32_e32 v238, v238, v239
	v_add_f32_e32 v14, v14, v168
	v_add_f32_e32 v198, v198, v238
	v_add_f32_e32 v235, v14, v198
	s_cmp_lg_u64 s[48:49], 0
	s_cbranch_scc0 .Lattn_noprio_near
	s_setprio 1
.Lattn_noprio_near:
.LBB0_217:
	s_and_b32 s6, s42, 0xc000
	s_addk_i32 s42, 0x4000
	s_add_i32 s7, s6, s64
	s_add_i32 s20, s84, s4
	s_and_b32 s5, s42, 0xc000
	v_add_u32_e32 v248, s6, v222
	v_add_u32_e32 v249, s6, v223
	s_add_i32 s10, s42, 0x8000
	s_and_b32 s10, s10, 0xc000
	s_add_i32 s10, s10, s65
	ds_read_b128 v[2:5], v248 offset:32768
	ds_read_b128 v[6:9], v248 offset:36864
	ds_read_b128 v[136:139], v248 offset:40960
	ds_read_b128 v[140:143], v248 offset:45056
	ds_read_b128 v[240:243], v249 offset:32768
	s_lshl_b64 s[8:9], s[20:21], 1
	s_mov_b32 m0, s7
	v_lshl_add_u64 v[236:237], v[194:195], 0, s[8:9]
	global_load_lds_dwordx4 v[12:13], off
	s_add_i32 m0, s7, 0x400
	v_add_u32_e32 v252, s5, v171
	global_load_lds_dwordx4 v[10:11], off
	s_add_i32 m0, s10, 0x10000
	v_add_u32_e32 v253, s5, v200
	global_load_lds_dwordx4 v[236:237], off
	v_lshl_add_u64 v[236:237], v[196:197], 0, s[8:9]
	s_add_i32 m0, s10, 0x10400
	v_add_u32_e32 v233, s5, v201
	global_load_lds_dwordx4 v[236:237], off
	v_add_u32_e32 v234, s5, v202
	v_add_u32_e32 v250, s6, v224
	v_add_u32_e32 v251, s6, v225
	v_add_f32_e32 v189, v189, v235
	v_add_u32_e32 v0, s84, v232
	v_exp_f32_e32 v14, v104
	v_exp_f32_e32 v15, v105
	v_exp_f32_e32 v168, v106
	v_exp_f32_e32 v169, v107
	v_exp_f32_e32 v198, v108
	v_exp_f32_e32 v199, v109
	v_exp_f32_e32 v238, v110
	v_exp_f32_e32 v239, v111
	s_waitcnt lgkmcnt(4)
	v_mfma_f32_32x32x16_bf16 v[64:79], v[2:5], v[128:131], v[64:79]
	ds_read_b128 v[244:247], v249 offset:36864
	v_cvt_pk_bf16_f32 v132, v14, v15
	v_cvt_pk_bf16_f32 v133, v168, v169
	v_add_f32_e32 v14, v14, v15
	v_add_f32_e32 v168, v168, v169
	v_add_u32_e32 v112, 0xc0, v0
	v_max_i32_e32 v112, 0, v112
	v_lshl_add_u32 v112, v112, 2, s61
	ds_read_b32 v96, v112
	v_add_u32_e32 v113, 0xc1, v0
	v_max_i32_e32 v113, 0, v113
	v_lshl_add_u32 v113, v113, 2, s61
	ds_read_b32 v97, v113
	s_waitcnt lgkmcnt(6)
	v_mfma_f32_32x32x16_bf16 v[48:63], v[6:9], v[128:131], v[48:63]
	ds_read_b128 v[2:5], v249 offset:40960
	v_cvt_pk_bf16_f32 v134, v198, v199
	v_cvt_pk_bf16_f32 v135, v238, v239
	v_add_f32_e32 v198, v198, v199
	v_add_f32_e32 v238, v238, v239
	v_add_u32_e32 v114, 0xc2, v0
	v_max_i32_e32 v114, 0, v114
	v_lshl_add_u32 v114, v114, 2, s61
	ds_read_b32 v98, v114
	v_add_u32_e32 v115, 0xc3, v0
	v_max_i32_e32 v115, 0, v115
	v_lshl_add_u32 v115, v115, 2, s61
	ds_read_b32 v99, v115
	s_waitcnt lgkmcnt(8)
	v_mfma_f32_32x32x16_bf16 v[32:47], v[136:139], v[128:131], v[32:47]
	ds_read_b128 v[6:9], v249 offset:45056
	v_add_f32_e32 v14, v14, v168
	v_add_f32_e32 v198, v198, v238
	v_add_f32_e32 v14, v14, v198
	v_add_f32_e32 v189, v189, v14
	v_add_u32_e32 v116, 0xc4, v0
	v_max_i32_e32 v116, 0, v116
	v_lshl_add_u32 v116, v116, 2, s61
	ds_read_b32 v100, v116
	v_add_u32_e32 v117, 0xc5, v0
	v_max_i32_e32 v117, 0, v117
	v_lshl_add_u32 v117, v117, 2, s61
	ds_read_b32 v101, v117
	s_waitcnt lgkmcnt(10)
	v_mfma_f32_32x32x16_bf16 v[16:31], v[140:143], v[128:131], v[16:31]
	ds_read_b128 v[136:139], v252
	v_exp_f32_e32 v14, v80
	v_exp_f32_e32 v15, v81
	v_exp_f32_e32 v168, v82
	v_add_u32_e32 v118, 0xc6, v0
	v_max_i32_e32 v118, 0, v118
	v_lshl_add_u32 v118, v118, 2, s61
	ds_read_b32 v102, v118
	v_add_u32_e32 v119, 0xc7, v0
	v_max_i32_e32 v119, 0, v119
	v_lshl_add_u32 v119, v119, 2, s61
	ds_read_b32 v103, v119
	v_add_u32_e32 v120, 0xd0, v0
	v_max_i32_e32 v120, 0, v120
	v_lshl_add_u32 v120, v120, 2, s61
	ds_read_b32 v104, v120
	s_waitcnt lgkmcnt(13)
	v_mfma_f32_32x32x16_bf16 v[64:79], v[240:243], v[132:135], v[64:79]
	ds_read_b128 v[140:143], v253
	v_exp_f32_e32 v169, v83
	v_exp_f32_e32 v198, v84
	v_exp_f32_e32 v199, v85
	v_add_u32_e32 v121, 0xd1, v0
	v_max_i32_e32 v121, 0, v121
	v_lshl_add_u32 v121, v121, 2, s61
	ds_read_b32 v105, v121
	v_add_u32_e32 v122, 0xd2, v0
	v_max_i32_e32 v122, 0, v122
	v_lshl_add_u32 v122, v122, 2, s61
	ds_read_b32 v106, v122
	v_add_u32_e32 v123, 0xd3, v0
	v_max_i32_e32 v123, 0, v123
	v_lshl_add_u32 v123, v123, 2, s61
	ds_read_b32 v107, v123
	s_waitcnt lgkmcnt(15)
	v_mfma_f32_32x32x16_bf16 v[48:63], v[244:247], v[132:135], v[48:63]
	ds_read_b128 v[240:243], v233
	v_exp_f32_e32 v238, v86
	v_exp_f32_e32 v239, v87
	v_cvt_pk_bf16_f32 v128, v14, v15
	v_add_u32_e32 v124, 0xd4, v0
	v_max_i32_e32 v124, 0, v124
	v_lshl_add_u32 v124, v124, 2, s61
	ds_read_b32 v108, v124
	v_add_u32_e32 v125, 0xd5, v0
	v_max_i32_e32 v125, 0, v125
	v_lshl_add_u32 v125, v125, 2, s61
	ds_read_b32 v109, v125
	s_waitcnt lgkmcnt(15)
; #define MFMA32(a, b, c) __builtin_amdgcn_mfma_f32_32x32x16_bf16((a), (b), (c), 0, 0, 0)
; #define AT_LOADV(t) do { AT_DMA(vg[0] + (t) * 64, ldsl + AT_V0 + ((t) & 1) * AT_KS + dw); AT_DMA(vg[1] + (t) * 64, ldsl + AT_V0 + ((t) & 1) * AT_KS + dw + 1024); } while (0)
; template <bool NEAR>
; DI void attn_qk(f32x16& s0, f32x16& s1, ldsp_t kb, const int* kro, const bf16x8* qf, int dtile, const float* tb2, int hi, int qg, int r32) {
;     bf16x8 a[8];
; #pragma unroll
;     for (int ks = 0; ks < 4; ++ks) { a[2 * ks] = *(const __attribute__((address_space(3))) bf16x8*)(kb + kro[ks]); a[2 * ks + 1] = *(const __attribute__((address_space(3))) bf16x8*)(kb + kro[ks] + 8192); }
;     if (!NEAR) {
;         const float c0 = tb2[0];
; #pragma unroll
;         for (int k = 0; k < 16; ++k) { s0[k] = c0; s1[k] = c0; }
;     } else {
;         const int base = dtile * 64 + 8 * hi - (qg & 1) * 32 - r32 + 128;
; #pragma unroll
;         for (int k = 0; k < 16; ++k) { const int i0 = base + (k & 7) + 16 * (k >> 3), i1 = i0 + 32; s0[k] = tb2[i0 < 0 ? 0 : i0]; s1[k] = tb2[i1 < 0 ? 0 : i1]; }
;     }
; #pragma unroll
;     for (int ks = 0; ks < 4; ++ks) { s0 = MFMA32(a[2 * ks], qf[ks], s0); s1 = MFMA32(a[2 * ks + 1], qf[ks], s1); }
; }
; DI void attn_pv(f32x16& s0, f32x16& s1, ldsp_t vb, const int* vro, f32x16* o, float& lsum) {
; #pragma unroll
;     for (int k = 0; k < 16; ++k) { s0[k] = __builtin_amdgcn_exp2f(s0[k]); s1[k] = __builtin_amdgcn_exp2f(s1[k]); }
;     float ps = 0.f;
; #pragma unroll
;     for (int k = 0; k < 16; ++k) ps += s0[k] + s1[k];
;     lsum += ps;
;     bf16x8 pk[4]; pk[0] = pack8(s0, 0); pk[1] = pack8(s0, 1); pk[2] = pack8(s1, 0); pk[3] = pack8(s1, 1);
; #pragma unroll
;     for (int kk = 0; kk < 4; ++kk)
; #pragma unroll
;         for (int et = 0; et < 4; ++et) {
;             const bf16x8 a = *(const __attribute__((address_space(3))) bf16x8*)(vb + vro[kk] + et * 4096);
;             o[et] = MFMA32(a, pk[kk], o[et]);
;         }
; }
; DI void attn_mfma_phase(PP P, int l, unsigned char* lds, int G, int cid) {
;     ...
;         for (; kt < 2 * j; ++kt) {
;             AT_LOADK(kt + 2); AT_LOADV(kt + 1);
;             attn_qk<true>(sn0, sn1, ldsl + ((kt + 1) & 1) * AT_KS, kro, qf, kt + 1 - mychunk, tb2, hi, qg, r32);
;             attn_pv(sc0, sc1, ldsl + (kt & 1) * AT_KS, vro, o, lsum);
;             sc0 = sn0; sc1 = sn1;
;             __syncthreads();
;         }
	v_mfma_f32_32x32x16_bf16 v[32:47], v[2:5], v[132:135], v[32:47]
	ds_read_b128 v[244:247], v234
	v_cvt_pk_bf16_f32 v129, v168, v169
	v_add_f32_e32 v14, v14, v15
	v_add_f32_e32 v168, v168, v169
	v_add_u32_e32 v126, 0xd6, v0
	v_max_i32_e32 v126, 0, v126
	v_lshl_add_u32 v126, v126, 2, s61
	ds_read_b32 v110, v126
	v_add_u32_e32 v127, 0xd7, v0
	v_max_i32_e32 v127, 0, v127
	v_lshl_add_u32 v127, v127, 2, s61
	ds_read_b32 v111, v127
	s_waitcnt lgkmcnt(15)
	v_mfma_f32_32x32x16_bf16 v[16:31], v[6:9], v[132:135], v[16:31]
	ds_read_b128 v[2:5], v250 offset:32768
	v_cvt_pk_bf16_f32 v130, v198, v199
	v_cvt_pk_bf16_f32 v131, v238, v239
	v_add_f32_e32 v198, v198, v199
	s_waitcnt lgkmcnt(1)
	v_mfma_f32_32x32x16_bf16 v[96:111], v[136:139], v[156:159], v[96:111]
	ds_read_b128 v[6:9], v250 offset:36864
	v_add_f32_e32 v238, v238, v239
	v_add_f32_e32 v14, v14, v168
	v_add_f32_e32 v198, v198, v238
	s_waitcnt lgkmcnt(11)
	v_mfma_f32_32x32x16_bf16 v[96:111], v[140:143], v[152:155], v[96:111]
	ds_read_b128 v[136:139], v250 offset:40960
	v_add_f32_e32 v14, v14, v198
	v_add_f32_e32 v189, v189, v14
	s_waitcnt lgkmcnt(8)
	v_mfma_f32_32x32x16_bf16 v[96:111], v[240:243], v[148:151], v[96:111]
	ds_read_b128 v[140:143], v250 offset:45056
	v_exp_f32_e32 v14, v88
	v_exp_f32_e32 v15, v89
	v_exp_f32_e32 v168, v90
	s_waitcnt lgkmcnt(6)
	v_mfma_f32_32x32x16_bf16 v[96:111], v[244:247], v[144:147], v[96:111]
	ds_read_b128 v[240:243], v251 offset:32768
	v_exp_f32_e32 v169, v91
	v_exp_f32_e32 v198, v92
	v_exp_f32_e32 v199, v93
	s_waitcnt lgkmcnt(4)
	v_mfma_f32_32x32x16_bf16 v[64:79], v[2:5], v[128:131], v[64:79]
	ds_read_b128 v[244:247], v251 offset:36864
	v_exp_f32_e32 v238, v94
	v_exp_f32_e32 v239, v95
	v_cvt_pk_bf16_f32 v132, v14, v15
	v_cvt_pk_bf16_f32 v133, v168, v169
	s_waitcnt lgkmcnt(4)
	v_mfma_f32_32x32x16_bf16 v[48:63], v[6:9], v[128:131], v[48:63]
	ds_read_b128 v[2:5], v251 offset:40960
	v_add_f32_e32 v14, v14, v15
	v_add_f32_e32 v168, v168, v169
	v_cvt_pk_bf16_f32 v134, v198, v199
	v_cvt_pk_bf16_f32 v135, v238, v239
	v_add_u32_e32 v112, 0xc0, v0
	v_max_i32_e32 v112, 0xffffffe0, v112
	v_lshl_add_u32 v112, v112, 2, s61
	ds_read_b32 v80, v112 offset:128
	v_add_u32_e32 v113, 0xc1, v0
	v_max_i32_e32 v113, 0xffffffe0, v113
	v_lshl_add_u32 v113, v113, 2, s61
	ds_read_b32 v81, v113 offset:128
	s_waitcnt lgkmcnt(6)
	v_mfma_f32_32x32x16_bf16 v[32:47], v[136:139], v[128:131], v[32:47]
	ds_read_b128 v[6:9], v251 offset:45056
	v_add_f32_e32 v198, v198, v199
	v_add_f32_e32 v238, v238, v239
	v_add_f32_e32 v14, v14, v168
	v_add_u32_e32 v114, 0xc2, v0
	v_max_i32_e32 v114, 0xffffffe0, v114
	v_lshl_add_u32 v114, v114, 2, s61
	ds_read_b32 v82, v114 offset:128
	v_add_u32_e32 v115, 0xc3, v0
	v_max_i32_e32 v115, 0xffffffe0, v115
	v_lshl_add_u32 v115, v115, 2, s61
	ds_read_b32 v83, v115 offset:128
	v_add_u32_e32 v116, 0xc4, v0
	v_max_i32_e32 v116, 0xffffffe0, v116
	v_lshl_add_u32 v116, v116, 2, s61
	ds_read_b32 v84, v116 offset:128
	s_waitcnt lgkmcnt(9)
	v_mfma_f32_32x32x16_bf16 v[16:31], v[140:143], v[128:131], v[16:31]
	ds_read_b128 v[136:139], v252 offset:8192
	v_add_f32_e32 v198, v198, v238
	v_add_f32_e32 v14, v14, v198
	v_add_f32_e32 v189, v189, v14
	v_add_u32_e32 v117, 0xc5, v0
	v_max_i32_e32 v117, 0xffffffe0, v117
	v_lshl_add_u32 v117, v117, 2, s61
	ds_read_b32 v85, v117 offset:128
	v_add_u32_e32 v118, 0xc6, v0
	v_max_i32_e32 v118, 0xffffffe0, v118
	v_lshl_add_u32 v118, v118, 2, s61
	ds_read_b32 v86, v118 offset:128
	v_add_u32_e32 v119, 0xc7, v0
	v_max_i32_e32 v119, 0xffffffe0, v119
	v_lshl_add_u32 v119, v119, 2, s61
	ds_read_b32 v87, v119 offset:128
	s_waitcnt lgkmcnt(12)
	v_mfma_f32_32x32x16_bf16 v[64:79], v[240:243], v[132:135], v[64:79]
	ds_read_b128 v[140:143], v253 offset:8192
	v_exp_f32_e32 v14, v96
	v_exp_f32_e32 v15, v97
	v_exp_f32_e32 v168, v98
	v_add_u32_e32 v120, 0xd0, v0
	v_max_i32_e32 v120, 0xffffffe0, v120
	v_lshl_add_u32 v120, v120, 2, s61
	ds_read_b32 v88, v120 offset:128
	v_add_u32_e32 v121, 0xd1, v0
	v_max_i32_e32 v121, 0xffffffe0, v121
	v_lshl_add_u32 v121, v121, 2, s61
	ds_read_b32 v89, v121 offset:128
	v_add_u32_e32 v122, 0xd2, v0
	v_max_i32_e32 v122, 0xffffffe0, v122
	v_lshl_add_u32 v122, v122, 2, s61
	ds_read_b32 v90, v122 offset:128
	s_waitcnt lgkmcnt(15)
	v_mfma_f32_32x32x16_bf16 v[48:63], v[244:247], v[132:135], v[48:63]
	ds_read_b128 v[240:243], v233 offset:8192
	v_exp_f32_e32 v169, v99
	v_exp_f32_e32 v198, v100
	v_exp_f32_e32 v199, v101
	v_add_u32_e32 v123, 0xd3, v0
	v_max_i32_e32 v123, 0xffffffe0, v123
	v_lshl_add_u32 v123, v123, 2, s61
	ds_read_b32 v91, v123 offset:128
	v_add_u32_e32 v124, 0xd4, v0
	v_max_i32_e32 v124, 0xffffffe0, v124
	v_lshl_add_u32 v124, v124, 2, s61
	ds_read_b32 v92, v124 offset:128
	v_add_u32_e32 v125, 0xd5, v0
	v_max_i32_e32 v125, 0xffffffe0, v125
	v_lshl_add_u32 v125, v125, 2, s61
	ds_read_b32 v93, v125 offset:128
	s_waitcnt lgkmcnt(15)
	v_mfma_f32_32x32x16_bf16 v[32:47], v[2:5], v[132:135], v[32:47]
	ds_read_b128 v[244:247], v234 offset:8192
	v_exp_f32_e32 v238, v102
	v_exp_f32_e32 v239, v103
	v_cvt_pk_bf16_f32 v128, v14, v15
	v_add_u32_e32 v126, 0xd6, v0
	v_max_i32_e32 v126, 0xffffffe0, v126
	v_lshl_add_u32 v126, v126, 2, s61
	ds_read_b32 v94, v126 offset:128
	v_add_u32_e32 v127, 0xd7, v0
	v_max_i32_e32 v127, 0xffffffe0, v127
	v_lshl_add_u32 v127, v127, 2, s61
	ds_read_b32 v95, v127 offset:128
	s_waitcnt lgkmcnt(15)
	v_mfma_f32_32x32x16_bf16 v[16:31], v[6:9], v[132:135], v[16:31]
	v_cvt_pk_bf16_f32 v129, v168, v169
	v_cvt_pk_bf16_f32 v130, v198, v199
	v_cvt_pk_bf16_f32 v131, v238, v239
	s_waitcnt lgkmcnt(0)
	v_mfma_f32_32x32x16_bf16 v[80:95], v[136:139], v[156:159], v[80:95]
	v_add_f32_e32 v14, v14, v15
	v_add_f32_e32 v168, v168, v169
	v_add_f32_e32 v198, v198, v199
	v_add_f32_e32 v238, v238, v239
	v_mfma_f32_32x32x16_bf16 v[80:95], v[140:143], v[152:155], v[80:95]
	v_add_f32_e32 v14, v14, v168
	v_add_f32_e32 v198, v198, v238
	v_add_f32_e32 v235, v14, v198
	s_waitcnt vmcnt(8) lgkmcnt(0)
	s_barrier
	v_mfma_f32_32x32x16_bf16 v[80:95], v[240:243], v[148:151], v[80:95]
	v_lshl_add_u64 v[12:13], v[12:13], 0, s[34:35]
	v_lshl_add_u64 v[10:11], v[10:11], 0, s[34:35]
	v_add_u32_e32 v232, 64, v232
	s_add_i32 s4, s4, 64
	s_add_i32 s38, s38, 1
	s_cmp_lt_i32 s38, s13
	v_mfma_f32_32x32x16_bf16 v[80:95], v[244:247], v[144:147], v[80:95]
	s_cbranch_scc1 .LBB0_217
	s_nop 11
	v_mov_b64_e32 v[142:143], v[94:95]
	v_mov_b64_e32 v[126:127], v[110:111]
	v_mov_b64_e32 v[140:141], v[92:93]
	v_mov_b64_e32 v[138:139], v[90:91]
	v_mov_b64_e32 v[136:137], v[88:89]
	v_mov_b64_e32 v[134:135], v[86:87]
	v_mov_b64_e32 v[132:133], v[84:85]
	v_mov_b64_e32 v[130:131], v[82:83]
	v_mov_b64_e32 v[128:129], v[80:81]
	v_mov_b64_e32 v[124:125], v[108:109]
	v_mov_b64_e32 v[122:123], v[106:107]
	v_mov_b64_e32 v[120:121], v[104:105]
	v_mov_b64_e32 v[118:119], v[102:103]
	v_mov_b64_e32 v[116:117], v[100:101]
	v_mov_b64_e32 v[114:115], v[98:99]
	v_mov_b64_e32 v[112:113], v[96:97]
; #define MFMA32(a, b, c) __builtin_amdgcn_mfma_f32_32x32x16_bf16((a), (b), (c), 0, 0, 0)
; #define AT_LOADV(t) do { AT_DMA(vg[0] + (t) * 64, ldsl + AT_V0 + ((t) & 1) * AT_KS + dw); AT_DMA(vg[1] + (t) * 64, ldsl + AT_V0 + ((t) & 1) * AT_KS + dw + 1024); } while (0)
; template <bool NEAR>
; DI void attn_qk(f32x16& s0, f32x16& s1, ldsp_t kb, const int* kro, const bf16x8* qf, int dtile, const float* tb2, int hi, int qg, int r32) {
;     bf16x8 a[8];
; #pragma unroll
;     for (int ks = 0; ks < 4; ++ks) { a[2 * ks] = *(const __attribute__((address_space(3))) bf16x8*)(kb + kro[ks]); a[2 * ks + 1] = *(const __attribute__((address_space(3))) bf16x8*)(kb + kro[ks] + 8192); }
;     if (!NEAR) {
;         const float c0 = tb2[0];
; #pragma unroll
;         for (int k = 0; k < 16; ++k) { s0[k] = c0; s1[k] = c0; }
;     } else {
;         const int base = dtile * 64 + 8 * hi - (qg & 1) * 32 - r32 + 128;
; #pragma unroll
;         for (int k = 0; k < 16; ++k) { const int i0 = base + (k & 7) + 16 * (k >> 3), i1 = i0 + 32; s0[k] = tb2[i0 < 0 ? 0 : i0]; s1[k] = tb2[i1 < 0 ? 0 : i1]; }
;     }
; #pragma unroll
;     for (int ks = 0; ks < 4; ++ks) { s0 = MFMA32(a[2 * ks], qf[ks], s0); s1 = MFMA32(a[2 * ks + 1], qf[ks], s1); }
; }
; DI void attn_mfma_phase(PP P, int l, unsigned char* lds, int G, int cid) {
;     ...
;         AT_LOADV(2 * j + 1);
;         if (qg >= 2) attn_qk<true>(sn0, sn1, ldsl + AT_KS, kro, qf, 0, tb2, hi, qg, r32);
;         attn_pv(sc0, sc1, ldsl, vro, o, lsum);
.LBB0_219:
	s_setprio 0
	s_and_b32 s4, s12, 0x80
	s_lshl_b32 s4, s4, 8
	v_cndmask_b32_e64 v0, 0, 1, s[44:45]
	v_add_u32_e32 v191, s4, v191
	v_cmp_ne_u32_e64 s[42:43], 1, v0
	v_add_u32_e32 v229, s4, v229
	v_add_u32_e32 v230, s4, v230
	v_add_u32_e32 v231, s4, v231
	s_andn2_b64 vcc, exec, s[44:45]
	s_cbranch_vccnz .LBB0_221
	ds_read_b128 v[2:5], v191 offset:16384
	ds_read_b128 v[6:9], v191 offset:24576
	ds_read2_b32 v[112:113], v217 offset1:1
	ds_read2_b32 v[114:115], v217 offset0:2 offset1:3
	ds_read2_b32 v[116:117], v217 offset0:4 offset1:5
	ds_read2_b32 v[118:119], v217 offset0:6 offset1:7
	ds_read2_b32 v[120:121], v217 offset0:16 offset1:17
	ds_read2_b32 v[122:123], v217 offset0:18 offset1:19
	ds_read2_b32 v[124:125], v217 offset0:20 offset1:21
	ds_read2_b32 v[126:127], v217 offset0:22 offset1:23
	ds_read2_b32 v[128:129], v217 offset0:32 offset1:33
	ds_read2_b32 v[130:131], v217 offset0:34 offset1:35
	ds_read2_b32 v[132:133], v217 offset0:36 offset1:37
	ds_read2_b32 v[134:135], v217 offset0:38 offset1:39
	ds_read2_b32 v[136:137], v217 offset0:48 offset1:49
	ds_read2_b32 v[138:139], v217 offset0:50 offset1:51
	ds_read2_b32 v[140:141], v217 offset0:52 offset1:53
	ds_read2_b32 v[142:143], v217 offset0:54 offset1:55
	s_waitcnt lgkmcnt(0)
	v_mfma_f32_32x32x16_bf16 v[112:127], v[2:5], v[156:159], v[112:127]
	v_mfma_f32_32x32x16_bf16 v[128:143], v[6:9], v[156:159], v[128:143]
	ds_read_b128 v[2:5], v229 offset:16384
	ds_read_b128 v[6:9], v229 offset:24576
	s_waitcnt lgkmcnt(0)
	v_mfma_f32_32x32x16_bf16 v[112:127], v[2:5], v[152:155], v[112:127]
	v_mfma_f32_32x32x16_bf16 v[128:143], v[6:9], v[152:155], v[128:143]
	ds_read_b128 v[2:5], v230 offset:16384
	ds_read_b128 v[6:9], v230 offset:24576
	s_waitcnt lgkmcnt(0)
	v_mfma_f32_32x32x16_bf16 v[112:127], v[2:5], v[148:151], v[112:127]
	v_mfma_f32_32x32x16_bf16 v[128:143], v[6:9], v[148:151], v[128:143]
	ds_read_b128 v[2:5], v231 offset:16384
	ds_read_b128 v[6:9], v231 offset:24576
	s_waitcnt lgkmcnt(0)
	v_mfma_f32_32x32x16_bf16 v[112:127], v[2:5], v[144:147], v[112:127]
	v_mfma_f32_32x32x16_bf16 v[128:143], v[6:9], v[144:147], v[128:143]
